# P3 static rebalance: CUs 0-127 take 3 uq tiles each, CUs 128-255 take 4 ukv tiles each (was 2+2 / 1+2)
# baseline (speedup 1.0000x reference)
.LBB0_418:
	s_add_u32 s8, s56, 0x13c00000
	s_addc_u32 s9, s57, 0
	s_add_u32 s12, s56, 0x18200000
	s_addc_u32 s13, s57, 0
	s_cmp_lt_i32 s58, 4
	s_cselect_b64 s[0:1], -1, 0
	s_cmp_gt_i32 s59, 3
	s_cselect_b64 s[4:5], -1, 0
	s_and_b64 s[6:7], s[0:1], s[4:5]
	s_andn2_b64 vcc, exec, s[6:7]
	s_cbranch_vccnz .LBB0_463
	v_lshlrev_b32_e32 v1, 4, v192
	v_and_b32_e32 v2, 32, v192
	v_bitop3_b32 v8, v1, v2, 48 bitop3:0x6c
	v_lshrrev_b32_e32 v2, 1, v192
	v_lshrrev_b32_e32 v4, 5, v192
	v_and_b32_e32 v2, 24, v2
	v_and_b32_e32 v4, 4, v4
	s_waitcnt lgkmcnt(0)
	v_bfe_u32 v5, v192, 2, 2
	v_bfe_u32 v3, v192, 2, 4
	v_or3_b32 v2, v4, v5, v2
	v_lshrrev_b32_e32 v4, 3, v192
	s_movk_i32 s1, 0x70
	v_and_or_b32 v158, v4, s1, v3
	s_movk_i32 s1, 0x60
	v_add_u32_e32 v1, 0x2000, v1
	v_and_or_b32 v159, v4, s1, v2
	v_lshrrev_b32_e32 v1, 7, v1
	s_movk_i32 s1, 0xf0
	v_bfe_u32 v0, v192, 4, 2
	v_and_or_b32 v160, v1, s1, v3
	s_movk_i32 s1, 0xe0
	v_and_or_b32 v161, v1, s1, v2
	v_lshlrev_b32_e32 v154, 3, v0
	v_lshlrev_b32_e32 v128, 4, v0
	v_lshlrev_b32_e32 v0, 6, v192
	v_lshlrev_b32_e32 v1, 2, v192
	v_and_b32_e32 v9, 64, v192
	v_and_b32_e32 v0, 0x3c0, v0
	v_and_b32_e32 v1, 32, v1
	s_ashr_i32 s30, s2, 31
	v_readfirstlane_b32 s0, v192
	v_or_b32_e32 v157, v8, v9
	v_and_b32_e32 v155, 15, v192
	s_cmpk_gt_i32 s2, 0x7f
	v_bitop3_b32 v156, v128, v1, v0 bitop3:0x36
	s_cbranch_scc1 .LBB0_439
	s_mul_hi_i32 s5, s2, 0x2aaaaaab
	s_lshr_b32 s10, s5, 31
	s_lshr_b32 s5, s5, 6
	s_add_i32 s5, s5, s10
	s_mulk_i32 s5, 0x180
	s_sub_i32 s5, s2, s5
	s_bfe_u32 s10, s5, 0x3001c
	s_add_i32 s10, s5, s10
	s_sext_i32_i16 s11, s10
	s_and_b32 s10, s10, 0xfff8
	s_lshr_b32 s4, s0, 6
	s_sub_i32 s5, s5, s10
	s_lshr_b32 s1, s0, 8
	s_lshl_b32 s34, s4, 10
	s_ashr_i32 s11, s11, 3
	s_sext_i32_i16 s10, s5
	s_cmp_lt_i32 s10, 0
	s_cselect_b32 s10, 49, 48
	s_mul_i32 s5, s5, s10
	s_add_i32 s5, s5, s11
	s_sext_i32_i16 s10, s5
	s_mulk_i32 s10, 0x2aab
	s_lshr_b32 s11, s10, 31
	s_ashr_i32 s10, s10, 18
	s_add_i32 s10, s10, s11
	s_lshl_b32 s11, s10, 3
	s_mul_i32 s10, s10, 24
	s_sub_i32 s10, s5, s10
	s_bfe_i32 s5, s10, 0x80000
	s_bfe_u32 s5, s5, 0x3000c
	s_add_i32 s14, s10, s5
	s_bfe_i32 s5, s14, 0x80000
	s_and_b32 s14, s14, 0xf8
	s_sub_i32 s10, s10, s14
	v_mul_u32_u24_e32 v0, 0x180, v161
	v_lshrrev_b32_e32 v1, 1, v157
	s_sext_i32_i16 s15, s5
	s_sext_i32_i8 s10, s10
	v_or_b32_e32 v0, v0, v1
	v_mul_u32_u24_e32 v10, 0x180, v160
	s_add_i32 s50, s11, s10
	s_ashr_i32 s10, s15, 3
	v_lshlrev_b32_e32 v130, 1, v0
	v_or_b32_e32 v0, v10, v1
	s_lshr_b32 s5, s15, 3
	s_mul_hi_i32 s11, s10, 0x30000
	s_mul_i32 s10, s10, 0x30000
	v_lshlrev_b32_e32 v132, 1, v0
	v_mul_u32_u24_e32 v0, 0x180, v159
	s_add_u32 s24, s86, s10
	v_or_b32_e32 v0, v0, v1
	s_addc_u32 s25, s87, s11
	s_add_i32 s35, s34, 0
	v_lshlrev_b32_e32 v134, 1, v0
	s_add_i32 m0, s35, 0x10000
	s_mul_i32 s18, s50, 0x30000
	global_load_lds_dwordx4 v134, s[24:25]
	s_add_i32 m0, s35, 0x12000
	s_add_u32 s10, s24, 0x18000
	global_load_lds_dwordx4 v130, s[24:25]
	s_addc_u32 s11, s25, 0
	s_add_i32 m0, s35, 0x14000
	v_mul_u32_u24_e32 v11, 0x180, v158
	global_load_lds_dwordx4 v134, s[10:11]
	s_add_i32 m0, s35, 0x16000
	s_mul_hi_i32 s14, s50, 0x30000
	s_add_u32 s26, s74, s18
	v_or_b32_e32 v0, v1, v11
	s_addc_u32 s27, s75, s14
	s_add_i32 s36, s35, 0x2000
	v_lshlrev_b32_e32 v136, 1, v0
	global_load_lds_dwordx4 v130, s[10:11]
	s_mov_b32 m0, s35
	s_add_u32 s10, s26, 0x18000
	global_load_lds_dwordx4 v136, s[26:27]
	s_mov_b32 m0, s36
	s_addc_u32 s11, s27, 0
	s_add_i32 s37, s35, 0x4000
	global_load_lds_dwordx4 v132, s[26:27]
	s_mov_b32 m0, s37
	s_add_i32 s38, s35, 0x6000
	global_load_lds_dwordx4 v136, s[10:11]
	s_mov_b32 m0, s38
	v_mov_b32_e32 v135, 0
	global_load_lds_dwordx4 v132, s[10:11]
	v_mov_b32_e32 v131, v135
	v_mov_b32_e32 v137, v135
	v_mov_b32_e32 v133, v135
	s_cmp_eq_u32 s1, 1
	s_mov_b32 s39, 0
	v_lshl_add_u64 v[6:7], s[24:25], 0, v[134:135]
	v_lshl_add_u64 v[4:5], s[24:25], 0, v[130:131]
	v_lshl_add_u64 v[0:1], s[26:27], 0, v[136:137]
	s_cselect_b64 s[10:11], -1, 0
	s_cmp_lg_u32 s1, 1
	v_lshl_add_u64 v[2:3], s[26:27], 0, v[132:133]
	s_cbranch_scc1 .LBB0_422
	s_barrier
.LBB0_422:
	s_mov_b64 s[14:15], 0x80
	s_lshl_b32 s4, s4, 5
	s_add_i32 m0, s35, 0x18000
	v_lshl_add_u64 v[6:7], v[6:7], 0, s[14:15]
	s_lshl_b32 s20, s1, 13
	s_and_b32 s4, s4, 0x60
	s_waitcnt vmcnt(2)
	s_barrier
	global_load_lds_dwordx4 v[6:7], off
	v_lshl_add_u64 v[4:5], v[4:5], 0, s[14:15]
	s_add_i32 m0, s35, 0x1a000
	s_add_i32 s40, s35, 0x8000
	s_add_i32 s41, s35, 0xa000
	global_load_lds_dwordx4 v[4:5], off
	v_lshl_add_u64 v[0:1], v[0:1], 0, s[14:15]
	s_mov_b32 m0, s40
	s_add_u32 s18, s24, 0x18080
	global_load_lds_dwordx4 v[0:1], off
	v_lshl_add_u64 v[0:1], v[2:3], 0, s[14:15]
	s_mov_b32 m0, s41
	s_addc_u32 s19, s25, 0
	global_load_lds_dwordx4 v[0:1], off
	s_add_i32 m0, s35, 0x1c000
	v_lshl_add_u64 v[0:1], s[18:19], 0, v[134:135]
	global_load_lds_dwordx4 v[0:1], off
	v_lshl_add_u64 v[0:1], s[18:19], 0, v[130:131]
	s_add_i32 m0, s35, 0x1e000
	v_mov_b32_e32 v129, v135
	global_load_lds_dwordx4 v[0:1], off
	v_lshlrev_b32_e32 v1, 2, v155
	v_lshl_or_b32 v0, v155, 6, v128
	v_and_b32_e32 v1, 32, v1
	v_lshl_or_b32 v162, s1, 6, v155
	v_bitop3_b32 v2, v0, s20, v1 bitop3:0xde
	s_cmpk_lt_u32 s0, 0x100
	v_lshl_add_u64 v[0:1], s[56:57], 0, v[128:129]
	s_mov_b64 s[0:1], 0xc00000
	v_lshl_add_u64 v[138:139], v[0:1], 0, s[0:1]
	v_add_u16_e32 v0, v8, v9
	s_waitcnt vmcnt(6)
	v_lshrrev_b16_e32 v0, 1, v0
	v_lshl_or_b32 v163, s4, 7, v156
	s_cselect_b64 s[18:19], -1, 0
	v_add_lshl_u32 v140, v11, v0, 1
	v_add_lshl_u32 v142, v10, v0, 1
	s_add_i32 s44, 0, 0x10000
	s_add_i32 s45, 0, 0x14000
	v_mbcnt_lo_u32_b32 v0, -1, 0
	s_sext_i32_i8 s51, s5
	s_ashr_i32 s42, s60, 31
	s_movk_i32 s43, 0x80
	v_or_b32_e32 v129, s4, v154
	v_mov_b32_e32 v141, v135
	v_mov_b32_e32 v143, v135
	v_mov_b64_e32 v[144:145], 0x180
	v_mov_b64_e32 v[146:147], 0x17f
	v_add_u32_e32 v164, s44, v163
	v_add_u32_e32 v165, s45, v163
	v_add_u32_e32 v166, 0, v2
	v_mbcnt_hi_u32_b32 v167, -1, v0
	v_mov_b32_e32 v168, 0x358637bd
	s_mov_b32 s46, 0xf800000
	v_mov_b32_e32 v169, 0x260
	s_movk_i32 s47, 0x600
	s_barrier
	s_branch .LBB0_425

.LBB0_439:
	s_sub_i32 s2, s2, 0x80
	s_cmpk_gt_u32 s2, 0x1ff
	v_readfirstlane_b32 s18, v192
	s_cbranch_scc1 .Lp3b_skip
	s_lshr_b32 s0, s30, 23
	s_add_i32 s0, s2, s0
	s_and_b32 s0, s0, 0xfffffe00
	s_sub_i32 s0, s2, s0
	s_sext_i32_i16 s1, s0
	s_bfe_u32 s1, s1, 0x3001c
	s_add_i32 s1, s0, s1
	s_and_b32 s4, s1, 0xfff8
	s_sub_i32 s5, s0, s4
	s_sext_i32_i16 s0, s5
	s_cmp_gt_i32 s0, -1
	s_sext_i32_i16 s10, s1
	s_cbranch_scc0 .LBB0_442
	s_lshl_b32 s4, s5, 6
	s_lshr_b32 s0, s10, 3
	s_cbranch_execz .LBB0_443
	s_branch .LBB0_444

.LBB0_446:
	s_lshl_b32 s5, s14, 5
	s_mov_b64 s[14:15], 0x80
	s_add_i32 m0, s65, 0x18000
	v_lshl_add_u64 v[6:7], v[6:7], 0, s[14:15]
	s_lshl_b32 s19, s1, 13
	s_and_b32 s22, s5, 0x60
	s_waitcnt vmcnt(2)
	s_barrier
	global_load_lds_dwordx4 v[6:7], off
	v_lshl_add_u64 v[4:5], v[4:5], 0, s[14:15]
	s_add_i32 m0, s65, 0x1a000
	s_add_i32 s70, s65, 0x8000
	s_add_i32 s71, s65, 0xa000
	global_load_lds_dwordx4 v[4:5], off
	v_lshl_add_u64 v[0:1], v[0:1], 0, s[14:15]
	s_mov_b32 m0, s70
	s_add_u32 s20, s34, 0x10080
	global_load_lds_dwordx4 v[0:1], off
	v_lshl_add_u64 v[0:1], v[2:3], 0, s[14:15]
	s_mov_b32 m0, s71
	s_addc_u32 s21, s35, 0
	global_load_lds_dwordx4 v[0:1], off
	s_add_i32 m0, s65, 0x1c000
	v_lshl_add_u64 v[0:1], s[20:21], 0, v[132:133]
	global_load_lds_dwordx4 v[0:1], off
	v_lshl_add_u64 v[0:1], s[20:21], 0, v[136:137]
	s_add_i32 m0, s65, 0x1e000
	v_mov_b32_e32 v129, v133
	global_load_lds_dwordx4 v[0:1], off
	v_lshlrev_b32_e32 v1, 2, v155
	v_lshl_or_b32 v0, v155, 6, v128
	v_and_b32_e32 v1, 32, v1
	s_sext_i32_i8 s5, s0
	v_lshl_or_b32 v146, s1, 6, v155
	v_bitop3_b32 v2, v0, s19, v1 bitop3:0xde
	s_waitcnt vmcnt(6)
	s_cmpk_lt_u32 s18, 0x100
	v_lshl_add_u64 v[0:1], s[56:57], 0, v[128:129]
	s_mov_b64 s[0:1], 0xe00000
	v_lshl_or_b32 v147, s22, 7, v156
	s_cselect_b64 s[18:19], -1, 0
	v_lshl_add_u64 v[128:129], v[0:1], 0, s[0:1]
	s_add_i32 s74, 0, 0x10000
	s_add_i32 s75, 0, 0x14000
	v_mbcnt_lo_u32_b32 v0, -1, 0
	s_ashr_i32 s72, s60, 31
	s_movk_i32 s73, 0x80
	v_or_b32_e32 v148, s22, v154
	v_mov_b64_e32 v[138:139], 0x200
	v_mov_b64_e32 v[140:141], 0x1ff
	v_add_u32_e32 v149, s74, v147
	v_add_u32_e32 v150, s75, v147
	v_add_u32_e32 v151, 0, v2
	v_mbcnt_hi_u32_b32 v152, -1, v0
	v_mov_b32_e32 v153, 0x358637bd
	s_mov_b32 s78, 0xf800000
	v_mov_b32_e32 v154, 0x260
	s_barrier
	s_branch .LBB0_449

.Lp3b_skip:
	s_add_i32 s2, s2, 0x80
